# K1-easy: FFN-up K-loop: 8 of 16 LDS-DMA loads use saddr form, drop 64-bit VALU adds
# speedup vs baseline: 1.0051x; 1.0051x over previous
; #define PG8_STAGE(bufoff, gbase, voff) do { _Pragma("unroll") for (int _i = 0; _i < 2; ++_i) \
;         __builtin_amdgcn_global_load_lds((const unsigned*)((const char*)(gbase) + (voff)[_i]), (PG8_LAS unsigned*)(lds + (bufoff) + ldsw + _i * 8192), 16, 0, 0); } while (0)
; #define PG8_LDA(dst, b, h) do { _Pragma("unroll") for (int m = 0; m < 4; ++m) _Pragma("unroll") for (int k = 0; k < 2; ++k) dst[m][k] = *(const PG8_LAS bf16x8*)(lds + PG8_SA(b, h) + aoff + m * 2048 + k * 1024); } while (0)
; #define PG8_LDB(dst, b, h) do { _Pragma("unroll") for (int n = 0; n < 2; ++n) _Pragma("unroll") for (int k = 0; k < 2; ++k) dst[n][k] = *(const PG8_LAS bf16x8*)(lds + PG8_SB(b, h) + boff + n * 2048 + k * 1024); } while (0)
; #define PG8_MMA(ai, bj, At, Bt) do { __builtin_amdgcn_s_setprio(1); _Pragma("unroll") for (int m = 0; m < 4; ++m) _Pragma("unroll") for (int n = 0; n < 2; ++n) _Pragma("unroll") for (int k = 0; k < 2; ++k) \
;         acc[ai][bj][m][n] = mma16<Epi::I8>(Bt[n][k], At[m][k], acc[ai][bj][m][n]); __builtin_amdgcn_s_setprio(0); } while (0)
; #define PG8_WAIT_V(n) asm volatile("s_waitcnt vmcnt(" #n ")" ::: "memory")
; #define PG8_WAIT_L(n) asm volatile("s_waitcnt lgkmcnt(" #n ")" ::: "memory")
; #define PG8_BAR __builtin_amdgcn_s_barrier()
; #define PG8_SCHED __builtin_amdgcn_sched_barrier(0)
; template <class Epi, class Sched, bool ALIGN_EPI = false, bool SP2 = false>
; __device__ __forceinline__ void gemm_phase(PG8_LAS unsigned char* lds, const Gemm g, const Sched& S, const Epi& E) {
;     ...
;             PG8_LDB(B0, 0, 0); PG8_LDB(B1, 0, 1); PG8_SCHED; PG8_LDA(At, 0, 0); PG8_STAGE(PG8_SA(1, 1), a1 + hstep, voffA);
;             PG8_WAIT_V(8); PG8_WAIT_L(0); PG8_BAR; PG8_MMA(0, 0, At, B0); PG8_MMA(0, 1, At, B1); PG8_BAR; PG8_SCHED;
;             PG8_LDA(At, 0, 1); PG8_STAGE(PG8_SB(0, 0), b2, voffB); PG8_STAGE(PG8_SB(0, 1), b2 + hstep, voffB); PG8_STAGE(PG8_SA(0, 0), a2, voffA);
;             PG8_WAIT_V(8); PG8_WAIT_L(0); PG8_BAR; PG8_MMA(1, 0, At, B0); PG8_MMA(1, 1, At, B1); PG8_BAR; PG8_SCHED;
.LBB0_80:
	s_add_u32 s8, s0, 0x100
	s_addc_u32 s9, s1, 0
	s_add_i32 vcc_hi, 0, 0x10000
	s_cmp_eq_u32 vcc_lo, 12
	s_cselect_b32 s13, s66, s9
	s_cselect_b32 s12, s67, s8
	s_cselect_b32 s7, s82, s97
	s_cselect_b32 s6, s83, s96
	s_add_i32 s4, 0, 0x14000
	v_add_u32_e32 v38, vcc_hi, v242
	v_add_u32_e32 v158, s4, v242
	ds_read_b128 v[18:21], v38
	ds_read_b128 v[22:25], v38 offset:1024
	ds_read_b128 v[34:37], v38 offset:2048
	ds_read_b128 v[38:41], v38 offset:3072
	ds_read_b128 v[130:133], v158
	ds_read_b128 v[134:137], v158 offset:1024
	ds_read_b128 v[154:157], v158 offset:2048
	ds_read_b128 v[158:161], v158 offset:3072
	s_add_i32 m0, s11, 0xc000
	ds_read_b128 v[162:165], v243
	ds_read_b128 v[166:169], v243 offset:1024
	ds_read_b128 v[170:173], v243 offset:2048
	ds_read_b128 v[174:177], v243 offset:3072
	ds_read_b128 v[178:181], v243 offset:4096
	ds_read_b128 v[182:185], v243 offset:5120
	ds_read_b128 v[186:189], v243 offset:6144
	ds_read_b128 v[190:193], v243 offset:7168
	global_load_lds_dwordx4 v216, s[0:1]
	s_add_i32 m0, s11, 0xe000
	s_nop 0
	global_load_lds_dwordx4 v218, s[0:1]
	s_waitcnt vmcnt(8)
	s_waitcnt lgkmcnt(0)
	s_barrier
	s_setprio 1
	s_waitcnt lgkmcnt(0)
	v_mfma_i32_16x16x64_i8 v[150:153], v[18:21], v[162:165], v[150:153]
	v_mfma_i32_16x16x64_i8 v[146:149], v[34:37], v[162:165], v[146:149]
	v_mfma_i32_16x16x64_i8 v[118:121], v[18:21], v[170:173], v[118:121]
	v_mfma_i32_16x16x64_i8 v[110:113], v[34:37], v[170:173], v[110:113]
	v_mfma_i32_16x16x64_i8 v[54:57], v[18:21], v[178:181], v[54:57]
	v_mfma_i32_16x16x64_i8 v[30:33], v[34:37], v[178:181], v[30:33]
	v_mfma_i32_16x16x64_i8 v[94:97], v[18:21], v[186:189], v[94:97]
	v_mfma_i32_16x16x64_i8 v[58:61], v[34:37], v[186:189], v[58:61]
	v_mfma_i32_16x16x64_i8 v[150:153], v[22:25], v[166:169], v[150:153]
	v_mfma_i32_16x16x64_i8 v[146:149], v[38:41], v[166:169], v[146:149]
	v_mfma_i32_16x16x64_i8 v[118:121], v[22:25], v[174:177], v[118:121]
	v_mfma_i32_16x16x64_i8 v[110:113], v[38:41], v[174:177], v[110:113]
	v_mfma_i32_16x16x64_i8 v[54:57], v[22:25], v[182:185], v[54:57]
	v_mfma_i32_16x16x64_i8 v[30:33], v[38:41], v[182:185], v[30:33]
	v_mfma_i32_16x16x64_i8 v[94:97], v[22:25], v[190:193], v[94:97]
	v_mfma_i32_16x16x64_i8 v[58:61], v[38:41], v[190:193], v[58:61]
	s_setprio 0
	s_setprio 1
	v_mfma_i32_16x16x64_i8 v[142:145], v[130:133], v[162:165], v[142:145]
	v_mfma_i32_16x16x64_i8 v[138:141], v[154:157], v[162:165], v[138:141]
	v_mfma_i32_16x16x64_i8 v[102:105], v[130:133], v[170:173], v[102:105]
	v_mfma_i32_16x16x64_i8 v[98:101], v[154:157], v[170:173], v[98:101]
	v_mfma_i32_16x16x64_i8 v[42:45], v[130:133], v[178:181], v[42:45]
	v_mfma_i32_16x16x64_i8 v[26:29], v[154:157], v[178:181], v[26:29]
	v_mfma_i32_16x16x64_i8 v[78:81], v[130:133], v[186:189], v[78:81]
	v_mfma_i32_16x16x64_i8 v[62:65], v[154:157], v[186:189], v[62:65]
	v_mfma_i32_16x16x64_i8 v[142:145], v[134:137], v[166:169], v[142:145]
	v_mfma_i32_16x16x64_i8 v[138:141], v[158:161], v[166:169], v[138:141]
	v_mfma_i32_16x16x64_i8 v[102:105], v[134:137], v[174:177], v[102:105]
	v_mfma_i32_16x16x64_i8 v[98:101], v[158:161], v[174:177], v[98:101]
	v_mfma_i32_16x16x64_i8 v[42:45], v[134:137], v[182:185], v[42:45]
	v_mfma_i32_16x16x64_i8 v[26:29], v[158:161], v[182:185], v[26:29]
	v_mfma_i32_16x16x64_i8 v[78:81], v[134:137], v[190:193], v[78:81]
	v_mfma_i32_16x16x64_i8 v[62:65], v[158:161], v[190:193], v[62:65]
	s_setprio 0
	s_barrier
	s_add_i32 s0, vcc_hi, s69
	v_lshl_add_u64 v[198:199], s[6:7], 0, v[0:1]
	s_mov_b32 m0, s0
	ds_read_b128 v[162:165], v243 offset:16384
	ds_read_b128 v[166:169], v243 offset:17408
	ds_read_b128 v[170:173], v243 offset:18432
	ds_read_b128 v[174:177], v243 offset:19456
	ds_read_b128 v[178:181], v243 offset:20480
	ds_read_b128 v[182:185], v243 offset:21504
	ds_read_b128 v[186:189], v243 offset:22528
	ds_read_b128 v[190:193], v243 offset:23552
	global_load_lds_dwordx4 v[198:199], off
	s_add_i32 m0, s0, 0x2000
	s_add_u32 s0, s6, 0x40000
	v_lshl_add_u64 v[200:201], s[6:7], 0, v[214:215]
	s_addc_u32 s1, s7, 0
	s_add_i32 s4, s4, s69
	global_load_lds_dwordx4 v[200:201], off
	s_mov_b32 m0, s4
	v_lshl_add_u64 v[206:207], s[12:13], 0, v[210:211]
	global_load_lds_dwordx4 v0, s[0:1]
	s_add_i32 m0, s4, 0x2000
	v_lshl_add_u64 v[220:221], s[12:13], 0, v[212:213]
	global_load_lds_dwordx4 v214, s[0:1]
	s_mov_b32 m0, s11
	s_nop 0
	global_load_lds_dwordx4 v[206:207], off
	s_mov_b32 m0, s71
	s_nop 0
	global_load_lds_dwordx4 v[220:221], off
	s_waitcnt vmcnt(8)
	s_waitcnt lgkmcnt(0)
	s_barrier
	s_setprio 1
	s_waitcnt lgkmcnt(0)
	v_mfma_i32_16x16x64_i8 v[106:109], v[18:21], v[162:165], v[106:109]
	v_mfma_i32_16x16x64_i8 v[46:49], v[34:37], v[162:165], v[46:49]
	v_mfma_i32_16x16x64_i8 v[14:17], v[18:21], v[170:173], v[14:17]
	v_mfma_i32_16x16x64_i8 v[6:9], v[34:37], v[170:173], v[6:9]
	v_mfma_i32_16x16x64_i8 v[90:93], v[18:21], v[178:181], v[90:93]
	v_mfma_i32_16x16x64_i8 v[86:89], v[34:37], v[178:181], v[86:89]
	v_mfma_i32_16x16x64_i8 v[18:21], v[18:21], v[186:189], v[126:129]
	v_mfma_i32_16x16x64_i8 v[106:109], v[22:25], v[166:169], v[106:109]
	v_mfma_i32_16x16x64_i8 v[46:49], v[38:41], v[166:169], v[46:49]
	v_mfma_i32_16x16x64_i8 v[14:17], v[22:25], v[174:177], v[14:17]
	v_mfma_i32_16x16x64_i8 v[6:9], v[38:41], v[174:177], v[6:9]
	v_mfma_i32_16x16x64_i8 v[90:93], v[22:25], v[182:185], v[90:93]
	v_mfma_i32_16x16x64_i8 v[86:89], v[38:41], v[182:185], v[86:89]
	v_mfma_i32_16x16x64_i8 v[18:21], v[22:25], v[190:193], v[18:21]
	v_mfma_i32_16x16x64_i8 v[22:25], v[34:37], v[186:189], v[66:69]
	v_mfma_i32_16x16x64_i8 v[22:25], v[38:41], v[190:193], v[22:25]
	s_setprio 0
	s_setprio 1
	v_mfma_i32_16x16x64_i8 v[38:41], v[154:157], v[162:165], v[50:53]
	v_mfma_i32_16x16x64_i8 v[50:53], v[130:133], v[178:181], v[82:85]
	v_mfma_i32_16x16x64_i8 v[82:85], v[134:137], v[182:185], v[50:53]
	v_mfma_i32_16x16x64_i8 v[50:53], v[154:157], v[178:181], v[74:77]
	v_mfma_i32_16x16x64_i8 v[74:77], v[158:161], v[182:185], v[50:53]
	v_mfma_i32_16x16x64_i8 v[50:53], v[130:133], v[186:189], v[122:125]
	v_mfma_i32_16x16x64_i8 v[10:13], v[130:133], v[170:173], v[10:13]
	v_mfma_i32_16x16x64_i8 v[2:5], v[154:157], v[170:173], v[2:5]
	v_mfma_i32_16x16x64_i8 v[122:125], v[134:137], v[190:193], v[50:53]
	v_mfma_i32_16x16x64_i8 v[50:53], v[154:157], v[186:189], v[70:73]
	v_mfma_i32_16x16x64_i8 v[34:37], v[130:133], v[162:165], v[114:117]
	v_mfma_i32_16x16x64_i8 v[10:13], v[134:137], v[174:177], v[10:13]
	v_mfma_i32_16x16x64_i8 v[2:5], v[158:161], v[174:177], v[2:5]
	v_mfma_i32_16x16x64_i8 v[70:73], v[158:161], v[190:193], v[50:53]
	v_mfma_i32_16x16x64_i8 v[34:37], v[134:137], v[166:169], v[34:37]
	v_mfma_i32_16x16x64_i8 v[38:41], v[158:161], v[166:169], v[38:41]
	s_setprio 0
	s_barrier
; #define PG8_STAGE(bufoff, gbase, voff) do { _Pragma("unroll") for (int _i = 0; _i < 2; ++_i) \
;         __builtin_amdgcn_global_load_lds((const unsigned*)((const char*)(gbase) + (voff)[_i]), (PG8_LAS unsigned*)(lds + (bufoff) + ldsw + _i * 8192), 16, 0, 0); } while (0)
; #define PG8_LDA(dst, b, h) do { _Pragma("unroll") for (int m = 0; m < 4; ++m) _Pragma("unroll") for (int k = 0; k < 2; ++k) dst[m][k] = *(const PG8_LAS bf16x8*)(lds + PG8_SA(b, h) + aoff + m * 2048 + k * 1024); } while (0)
; #define PG8_LDB(dst, b, h) do { _Pragma("unroll") for (int n = 0; n < 2; ++n) _Pragma("unroll") for (int k = 0; k < 2; ++k) dst[n][k] = *(const PG8_LAS bf16x8*)(lds + PG8_SB(b, h) + boff + n * 2048 + k * 1024); } while (0)
; #define PG8_MMA(ai, bj, At, Bt) do { __builtin_amdgcn_s_setprio(1); _Pragma("unroll") for (int m = 0; m < 4; ++m) _Pragma("unroll") for (int n = 0; n < 2; ++n) _Pragma("unroll") for (int k = 0; k < 2; ++k) \
;         acc[ai][bj][m][n] = mma16<Epi::I8>(Bt[n][k], At[m][k], acc[ai][bj][m][n]); __builtin_amdgcn_s_setprio(0); } while (0)
; #define PG8_WAIT_V(n) asm volatile("s_waitcnt vmcnt(" #n ")" ::: "memory")
; #define PG8_WAIT_L(n) asm volatile("s_waitcnt lgkmcnt(" #n ")" ::: "memory")
; #define PG8_BAR __builtin_amdgcn_s_barrier()
; #define PG8_SCHED __builtin_amdgcn_sched_barrier(0)
; template <class Epi, class Sched, bool ALIGN_EPI = false, bool SP2 = false>
; __device__ __forceinline__ void gemm_phase(PG8_LAS unsigned char* lds, const Gemm g, const Sched& S, const Epi& E) {
;     ...
;         for (int t = 0; t < nt; t += 2) {
;     ...
;             PG8_LDB(B0, 1, 0); PG8_LDB(B1, 1, 1); PG8_SCHED; PG8_LDA(At, 1, 0); PG8_STAGE(PG8_SA(0, 1), a2 + hstep, voffA);
;             PG8_WAIT_V(8); PG8_WAIT_L(0); PG8_BAR; PG8_MMA(0, 0, At, B0); PG8_MMA(0, 1, At, B1); PG8_BAR; PG8_SCHED;
;             PG8_LDA(At, 1, 1); PG8_STAGE(PG8_SB(1, 0), b3, voffB); PG8_STAGE(PG8_SB(1, 1), b3 + hstep, voffB); PG8_STAGE(PG8_SA(1, 0), a3, voffA);
;             PG8_WAIT_V(8); PG8_WAIT_L(0); PG8_BAR; PG8_MMA(1, 0, At, B0); PG8_MMA(1, 1, At, B1); PG8_BAR; PG8_SCHED;
;     ...
;         if constexpr (ALIGN_EPI) { if (wr == 0) PG8_BAR; }
	s_add_i32 s4, 0, 0x18000
	v_add_u32_e32 v126, s4, v242
	s_add_i32 s5, 0, 0x1c000
	ds_read_b128 v[50:53], v126
	ds_read_b128 v[66:69], v126 offset:1024
	ds_read_b128 v[114:117], v126 offset:2048
	ds_read_b128 v[130:133], v126 offset:3072
	v_add_u32_e32 v126, s5, v242
	ds_read_b128 v[134:137], v126
	ds_read_b128 v[154:157], v126 offset:1024
	ds_read_b128 v[158:161], v126 offset:2048
	ds_read_b128 v[162:165], v126 offset:3072
	s_add_u32 s0, s12, 0x40000
	s_addc_u32 s1, s13, 0
	s_mov_b32 m0, s80
	ds_read_b128 v[126:129], v243 offset:32768
	ds_read_b128 v[166:169], v243 offset:33792
	ds_read_b128 v[170:173], v243 offset:34816
	ds_read_b128 v[174:177], v243 offset:35840
	ds_read_b128 v[178:181], v243 offset:36864
	ds_read_b128 v[182:185], v243 offset:37888
	ds_read_b128 v[186:189], v243 offset:38912
	ds_read_b128 v[190:193], v243 offset:39936
	global_load_lds_dwordx4 v210, s[0:1]
	s_mov_b32 m0, s81
	s_nop 0
	global_load_lds_dwordx4 v212, s[0:1]
	s_waitcnt vmcnt(8)
	s_waitcnt lgkmcnt(0)
	s_barrier
	s_setprio 1
	s_waitcnt lgkmcnt(0)
	v_mfma_i32_16x16x64_i8 v[150:153], v[50:53], v[126:129], v[150:153]
	v_mfma_i32_16x16x64_i8 v[146:149], v[114:117], v[126:129], v[146:149]
	v_mfma_i32_16x16x64_i8 v[118:121], v[50:53], v[170:173], v[118:121]
	v_mfma_i32_16x16x64_i8 v[110:113], v[114:117], v[170:173], v[110:113]
	v_mfma_i32_16x16x64_i8 v[54:57], v[50:53], v[178:181], v[54:57]
	v_mfma_i32_16x16x64_i8 v[30:33], v[114:117], v[178:181], v[30:33]
	v_mfma_i32_16x16x64_i8 v[94:97], v[50:53], v[186:189], v[94:97]
	v_mfma_i32_16x16x64_i8 v[58:61], v[114:117], v[186:189], v[58:61]
	v_mfma_i32_16x16x64_i8 v[150:153], v[66:69], v[166:169], v[150:153]
	v_mfma_i32_16x16x64_i8 v[146:149], v[130:133], v[166:169], v[146:149]
	v_mfma_i32_16x16x64_i8 v[118:121], v[66:69], v[174:177], v[118:121]
	v_mfma_i32_16x16x64_i8 v[110:113], v[130:133], v[174:177], v[110:113]
	v_mfma_i32_16x16x64_i8 v[54:57], v[66:69], v[182:185], v[54:57]
	v_mfma_i32_16x16x64_i8 v[30:33], v[130:133], v[182:185], v[30:33]
	v_mfma_i32_16x16x64_i8 v[94:97], v[66:69], v[190:193], v[94:97]
	v_mfma_i32_16x16x64_i8 v[58:61], v[130:133], v[190:193], v[58:61]
	s_setprio 0
	s_setprio 1
	v_mfma_i32_16x16x64_i8 v[142:145], v[134:137], v[126:129], v[142:145]
	v_mfma_i32_16x16x64_i8 v[126:129], v[158:161], v[126:129], v[138:141]
	v_mfma_i32_16x16x64_i8 v[102:105], v[134:137], v[170:173], v[102:105]
	v_mfma_i32_16x16x64_i8 v[98:101], v[158:161], v[170:173], v[98:101]
	v_mfma_i32_16x16x64_i8 v[42:45], v[134:137], v[178:181], v[42:45]
	v_mfma_i32_16x16x64_i8 v[26:29], v[158:161], v[178:181], v[26:29]
	v_mfma_i32_16x16x64_i8 v[78:81], v[134:137], v[186:189], v[78:81]
	v_mfma_i32_16x16x64_i8 v[62:65], v[158:161], v[186:189], v[62:65]
	v_mfma_i32_16x16x64_i8 v[142:145], v[154:157], v[166:169], v[142:145]
	v_mfma_i32_16x16x64_i8 v[138:141], v[162:165], v[166:169], v[126:129]
	v_mfma_i32_16x16x64_i8 v[102:105], v[154:157], v[174:177], v[102:105]
	v_mfma_i32_16x16x64_i8 v[98:101], v[162:165], v[174:177], v[98:101]
	v_mfma_i32_16x16x64_i8 v[42:45], v[154:157], v[182:185], v[42:45]
	v_mfma_i32_16x16x64_i8 v[26:29], v[162:165], v[182:185], v[26:29]
	v_mfma_i32_16x16x64_i8 v[78:81], v[154:157], v[190:193], v[78:81]
	v_mfma_i32_16x16x64_i8 v[62:65], v[162:165], v[190:193], v[62:65]
	s_setprio 0
	s_barrier
	s_add_i32 s0, s4, s69
	v_lshl_add_u64 v[126:127], v[198:199], 0, s[92:93]
	s_mov_b32 m0, s0
	ds_read_b128 v[166:169], v243 offset:49152
	ds_read_b128 v[170:173], v243 offset:50176
	ds_read_b128 v[174:177], v243 offset:51200
	ds_read_b128 v[178:181], v243 offset:52224
	ds_read_b128 v[182:185], v243 offset:53248
	ds_read_b128 v[186:189], v243 offset:54272
	ds_read_b128 v[190:193], v243 offset:55296
	ds_read_b128 v[194:197], v243 offset:56320
	global_load_lds_dwordx4 v[126:127], off
	s_add_i32 m0, s0, 0x2000
	s_add_u32 s0, s6, 0x40080
	v_lshl_add_u64 v[126:127], v[200:201], 0, s[92:93]
	s_addc_u32 s1, s7, 0
	s_add_i32 s4, s5, s69
	global_load_lds_dwordx4 v[126:127], off
	s_mov_b32 m0, s4
	s_nop 0
	global_load_lds_dwordx4 v0, s[0:1]
	s_add_i32 m0, s4, 0x2000
	s_nop 0
	global_load_lds_dwordx4 v214, s[0:1]
	v_lshl_add_u64 v[126:127], v[206:207], 0, s[92:93]
	s_mov_b32 m0, s84
	s_nop 0
	global_load_lds_dwordx4 v[126:127], off
	v_lshl_add_u64 v[126:127], v[220:221], 0, s[92:93]
	s_mov_b32 m0, s85
	s_nop 0
	global_load_lds_dwordx4 v[126:127], off
	s_waitcnt vmcnt(8)
	s_waitcnt lgkmcnt(0)
	s_barrier
	s_setprio 1
	s_waitcnt lgkmcnt(0)
	v_mfma_i32_16x16x64_i8 v[18:21], v[50:53], v[190:193], v[18:21]
	v_mfma_i32_16x16x64_i8 v[106:109], v[50:53], v[166:169], v[106:109]
	v_mfma_i32_16x16x64_i8 v[46:49], v[114:117], v[166:169], v[46:49]
	v_mfma_i32_16x16x64_i8 v[14:17], v[50:53], v[174:177], v[14:17]
	v_mfma_i32_16x16x64_i8 v[6:9], v[114:117], v[174:177], v[6:9]
	v_mfma_i32_16x16x64_i8 v[90:93], v[50:53], v[182:185], v[90:93]
	v_mfma_i32_16x16x64_i8 v[86:89], v[114:117], v[182:185], v[86:89]
	v_mfma_i32_16x16x64_i8 v[126:129], v[66:69], v[194:197], v[18:21]
	v_mfma_i32_16x16x64_i8 v[18:21], v[114:117], v[190:193], v[22:25]
	v_mfma_i32_16x16x64_i8 v[106:109], v[66:69], v[170:173], v[106:109]
	v_mfma_i32_16x16x64_i8 v[46:49], v[130:133], v[170:173], v[46:49]
	v_mfma_i32_16x16x64_i8 v[14:17], v[66:69], v[178:181], v[14:17]
	v_mfma_i32_16x16x64_i8 v[6:9], v[130:133], v[178:181], v[6:9]
	v_mfma_i32_16x16x64_i8 v[90:93], v[66:69], v[186:189], v[90:93]
	v_mfma_i32_16x16x64_i8 v[86:89], v[130:133], v[186:189], v[86:89]
	v_mfma_i32_16x16x64_i8 v[66:69], v[130:133], v[194:197], v[18:21]
	s_setprio 0
	s_setprio 1
	v_mfma_i32_16x16x64_i8 v[18:21], v[134:137], v[166:169], v[34:37]
	v_mfma_i32_16x16x64_i8 v[114:117], v[154:157], v[170:173], v[18:21]
	v_mfma_i32_16x16x64_i8 v[18:21], v[158:161], v[166:169], v[38:41]
	v_mfma_i32_16x16x64_i8 v[50:53], v[162:165], v[170:173], v[18:21]
	v_mfma_i32_16x16x64_i8 v[18:21], v[134:137], v[182:185], v[82:85]
	v_mfma_i32_16x16x64_i8 v[82:85], v[154:157], v[186:189], v[18:21]
	v_mfma_i32_16x16x64_i8 v[18:21], v[158:161], v[182:185], v[74:77]
	v_mfma_i32_16x16x64_i8 v[74:77], v[162:165], v[186:189], v[18:21]
	v_mfma_i32_16x16x64_i8 v[18:21], v[134:137], v[190:193], v[122:125]
	v_mfma_i32_16x16x64_i8 v[10:13], v[134:137], v[174:177], v[10:13]
	v_mfma_i32_16x16x64_i8 v[2:5], v[158:161], v[174:177], v[2:5]
	v_mfma_i32_16x16x64_i8 v[122:125], v[154:157], v[194:197], v[18:21]
	v_mfma_i32_16x16x64_i8 v[18:21], v[158:161], v[190:193], v[70:73]
	v_mfma_i32_16x16x64_i8 v[10:13], v[154:157], v[178:181], v[10:13]
	v_mfma_i32_16x16x64_i8 v[2:5], v[162:165], v[178:181], v[2:5]
	v_mfma_i32_16x16x64_i8 v[70:73], v[162:165], v[194:197], v[18:21]
	s_setprio 0
	s_barrier
	s_add_i32 vcc_lo, vcc_lo, 2
	s_add_u32 s96, s96, 0x100
	s_addc_u32 s97, s97, 0
	s_cmp_gt_u32 vcc_lo, 13
	s_mov_b64 s[0:1], s[8:9]
	s_cbranch_scc0 .LBB0_80
	v_readlane_b32 s0, v254, 44
	v_readlane_b32 s1, v254, 45
	s_and_b64 vcc, exec, s[0:1]
	s_cbranch_vccz .LBB0_83
	s_barrier
